# prologue transpose loop: LDS tile double-buffered, one s_barrier per tile instead of two
# baseline (speedup 1.0000x reference)
; DI unsigned pk2(float lo, float hi) { f32x2 v = {lo, hi}; hbf2 r = __builtin_convertvector(v, hbf2); return __builtin_bit_cast(unsigned, r); }
; #define TR_BAR() do { asm volatile("s_waitcnt lgkmcnt(0)" ::: "memory"); __builtin_amdgcn_s_barrier(); asm volatile("" ::: "memory"); } while (0)
; DI void prologue(const Params& P, LAS unsigned char* lds) {
;     ...
;       while (t < NL * C8) {
;           const f32x4 a = v0 * g0, b = v1 * g1;
;           bf16_t* const dcur = dp;
;           const int tn_ = t + G; g0 = 1.f; g1 = 1.f;
;           if (tn_ < NL * C8) { TR_ADDR(tn_, s0, gp, dp, sN); v0 = *(const f32x4*)s0; v1 = *(const f32x4*)(s0 + (size_t)32 * sN); if (gp) { g0 = gp[0]; g1 = gp[32]; } }
;           tile[ty * 65 + 4 * tx] = a[0]; tile[ty * 65 + 4 * tx + 1] = a[1]; tile[ty * 65 + 4 * tx + 2] = a[2]; tile[ty * 65 + 4 * tx + 3] = a[3];
;           tile[(ty + 32) * 65 + 4 * tx] = b[0]; tile[(ty + 32) * 65 + 4 * tx + 1] = b[1]; tile[(ty + 32) * 65 + 4 * tx + 2] = b[2]; tile[(ty + 32) * 65 + 4 * tx + 3] = b[3];
;           TR_BAR();
;           { float e[8];
; #pragma unroll
;             for (int j = 0; j < 8; ++j) e[j] = tile[(8 * skp + j) * 65 + sn];
;             u32x4 w; w.x = pk2(e[0], e[1]); w.y = pk2(e[2], e[3]); w.z = pk2(e[4], e[5]); w.w = pk2(e[6], e[7]);
;             *(u32x4*)dcur = w; }
;           TR_BAR();
;           t = tn_;
;       }
.LBB0_53:
	v_pk_mul_f32 v[6:7], v[6:7], v[24:25] op_sel_hi:[1,0]
	v_pk_mul_f32 v[8:9], v[8:9], v[24:25] op_sel_hi:[1,0]
	v_pk_mul_f32 v[2:3], v[2:3], v[22:23] op_sel_hi:[1,0]
	ds_write2_b32 v23, v6, v7 offset1:1
	ds_write2_b32 v23, v8, v9 offset0:2 offset1:3
	v_add_u32_e32 v6, 0x2080, v23
	v_pk_mul_f32 v[4:5], v[4:5], v[22:23] op_sel_hi:[1,0]
	ds_write2_b32 v6, v2, v3 offset1:1
	v_add_u32_e32 v2, 0x2088, v23
	ds_write2_b32 v2, v4, v5 offset1:1
	s_waitcnt lgkmcnt(0)
	s_barrier
	v_add_u32_e32 v8, 0x400, v32
	ds_read2_b32 v[2:3], v32 offset1:65
	ds_read2_b32 v[4:5], v32 offset0:130 offset1:195
	ds_read2_b32 v[6:7], v8 offset0:4 offset1:69
	ds_read2_b32 v[8:9], v8 offset0:134 offset1:199
	s_andn2_b64 vcc, exec, s[0:1]
	s_waitcnt vmcnt(1)
	v_mov_b32_e32 v24, v33
	s_waitcnt lgkmcnt(3)
	v_cvt_pk_bf16_f32 v2, v2, v3
	s_waitcnt lgkmcnt(2)
	v_cvt_pk_bf16_f32 v3, v4, v5
	s_waitcnt lgkmcnt(1)
	v_cvt_pk_bf16_f32 v4, v6, v7
	s_waitcnt lgkmcnt(0)
	v_cvt_pk_bf16_f32 v5, v8, v9
	global_store_dwordx4 v[28:29], v[2:5], off
	s_waitcnt lgkmcnt(0)
	v_xor_b32_e32 v23, 0x8000, v23
	v_xor_b32_e32 v32, 0x8000, v32
	v_mov_b64_e32 v[6:7], v[10:11]
	s_waitcnt vmcnt(1)
	v_mov_b64_e32 v[2:3], v[14:15]
	v_mov_b64_e32 v[28:29], v[30:31]
	v_mov_b64_e32 v[8:9], v[12:13]
	v_mov_b64_e32 v[4:5], v[16:17]
	v_mov_b32_e32 v22, v34
	s_cbranch_vccz .LBB0_89
